# grid barrier: acquire-side L1 invalidate issued when the workgroup parks (after its arrival atomic) so it overlaps write-back/arrival/polling; no invalidate after release
# speedup vs baseline: 1.0169x; 1.0169x over previous
.LBB0_60:
	s_or_b64 exec, exec, s[8:9]
	v_cvt_f32_u32_e32 v4, v2
	s_waitcnt vmcnt(0)
	buffer_inv sc1
	v_readfirstlane_b32 s3, v3
	v_sub_u32_e32 v3, 0, v2
	v_rcp_iflag_f32_e32 v4, v4
	v_add_u32_e32 v5, s3, v1
	v_mul_f32_e32 v4, 0x4f7ffffe, v4
	v_cvt_u32_f32_e32 v4, v4
	v_mul_lo_u32 v1, v3, v4
	v_mul_hi_u32 v1, v4, v1
	v_add_u32_e32 v1, v4, v1
	v_mul_hi_u32 v1, v5, v1
	v_mul_lo_u32 v3, v1, v2
	v_sub_u32_e32 v3, v5, v3
	v_add_u32_e32 v4, 1, v1
	v_cmp_ge_u32_e32 vcc, v3, v2
	s_nop 1
	v_cndmask_b32_e32 v1, v1, v4, vcc
	v_sub_u32_e32 v4, v3, v2
	v_cndmask_b32_e32 v3, v3, v4, vcc
	v_add_u32_e32 v4, 1, v1
	v_cmp_ge_u32_e32 vcc, v3, v2
	v_add_u32_e32 v3, 1, v5
	s_nop 0
	v_cndmask_b32_e32 v1, v1, v4, vcc
	v_mul_lo_u32 v4, v2, v1
	v_add_u32_e32 v2, v4, v2
	v_cmp_ne_u32_e32 vcc, v3, v2
	s_and_saveexec_b64 s[6:7], vcc
	s_xor_b64 s[6:7], exec, s[6:7]
	s_cbranch_execz .LBB0_74
	s_waitcnt lgkmcnt(0)
	v_add_u32_e32 v1, 1, v1
	v_mul_lo_u32 v1, v1, v0
	s_add_u32 s12, s24, 0xed25400
	s_addc_u32 s13, s25, 0
	v_mov_b32_e32 v0, 0
	global_load_dword v0, v0, s[12:13] sc1
	s_waitcnt vmcnt(0)
	v_cmp_lt_u32_e32 vcc, v0, v1
	s_and_saveexec_b64 s[8:9], vcc
	s_cbranch_execz .LBB0_73
	s_add_u32 s10, s24, 0xed22200
	s_addc_u32 s11, s25, 0
	s_mov_b32 s3, 1
	s_mov_b64 s[14:15], 0
	v_mov_b32_e32 v0, 0
	s_branch .LBB0_64

.LBB0_73:
	s_or_b64 exec, exec, s[8:9]
	s_waitcnt vmcnt(0)
	s_waitcnt vmcnt(0)

.LBB0_91:
	s_or_b64 exec, exec, s[6:7]
	s_mov_b64 s[6:7], exec
	v_mbcnt_lo_u32_b32 v0, s6, 0
	v_mbcnt_hi_u32_b32 v0, s7, v0
	v_cmp_eq_u32_e32 vcc, 0, v0
	s_waitcnt vmcnt(0)
	s_and_saveexec_b64 s[8:9], vcc
	s_cbranch_execz .LBB0_93
	s_bcnt1_i32_b64 s3, s[6:7]
	v_mov_b32_e32 v0, 0x2000
	v_mov_b32_e32 v1, s3

.LBB0_219:
	s_or_b64 exec, exec, s[8:9]
	s_mov_b64 s[8:9], exec
	v_mbcnt_lo_u32_b32 v0, s8, 0
	v_mbcnt_hi_u32_b32 v0, s9, v0
	v_cmp_eq_u32_e32 vcc, 0, v0
	s_waitcnt vmcnt(0)
	s_and_saveexec_b64 s[10:11], vcc
	s_cbranch_execz .LBB0_221
	s_bcnt1_i32_b64 s3, s[8:9]
	v_mov_b32_e32 v0, 0x2000
	v_mov_b32_e32 v1, s3

.LBB0_954:
	s_or_b64 exec, exec, s[12:13]
	v_cvt_f32_u32_e32 v4, v2
	s_waitcnt vmcnt(0)
	buffer_inv sc1
	v_readfirstlane_b32 s3, v3
	v_sub_u32_e32 v3, 0, v2
	v_rcp_iflag_f32_e32 v4, v4
	v_add_u32_e32 v5, s3, v1
	v_mul_f32_e32 v4, 0x4f7ffffe, v4
	v_cvt_u32_f32_e32 v4, v4
	v_mul_lo_u32 v1, v3, v4
	v_mul_hi_u32 v1, v4, v1
	v_add_u32_e32 v1, v4, v1
	v_mul_hi_u32 v1, v5, v1
	v_mul_lo_u32 v3, v1, v2
	v_sub_u32_e32 v3, v5, v3
	v_add_u32_e32 v4, 1, v1
	v_cmp_ge_u32_e32 vcc, v3, v2
	s_nop 1
	v_cndmask_b32_e32 v1, v1, v4, vcc
	v_sub_u32_e32 v4, v3, v2
	v_cndmask_b32_e32 v3, v3, v4, vcc
	v_add_u32_e32 v4, 1, v1
	v_cmp_ge_u32_e32 vcc, v3, v2
	v_add_u32_e32 v3, 1, v5
	s_nop 0
	v_cndmask_b32_e32 v1, v1, v4, vcc
	v_mul_lo_u32 v4, v2, v1
	v_add_u32_e32 v2, v4, v2
	v_cmp_ne_u32_e32 vcc, v3, v2
	s_and_saveexec_b64 s[10:11], vcc
	s_xor_b64 s[10:11], exec, s[10:11]
	s_cbranch_execz .LBB0_968
	s_waitcnt lgkmcnt(0)
	v_add_u32_e32 v1, 1, v1
	v_mul_lo_u32 v1, v1, v0
	s_add_u32 s42, s24, 0xed25400
	s_addc_u32 s43, s25, 0
	v_mov_b32_e32 v0, 0
	global_load_dword v0, v0, s[42:43] sc1
	s_waitcnt vmcnt(0)
	v_cmp_lt_u32_e32 vcc, v0, v1
	s_and_saveexec_b64 s[12:13], vcc
	s_cbranch_execz .LBB0_967
	s_add_u32 s40, s24, 0xed22200
	s_addc_u32 s41, s25, 0
	s_mov_b32 s3, 1
	s_mov_b64 s[46:47], 0
	v_mov_b32_e32 v0, 0
	s_branch .LBB0_958

.LBB0_967:
	s_or_b64 exec, exec, s[12:13]
	s_waitcnt vmcnt(0)
	s_waitcnt vmcnt(0)

.LBB0_985:
	s_or_b64 exec, exec, s[12:13]
	s_mov_b64 s[12:13], exec
	v_mbcnt_lo_u32_b32 v0, s12, 0
	v_mbcnt_hi_u32_b32 v0, s13, v0
	v_cmp_eq_u32_e32 vcc, 0, v0
	s_waitcnt vmcnt(0)
	s_and_saveexec_b64 s[16:17], vcc
	s_cbranch_execz .LBB0_987
	s_bcnt1_i32_b64 s3, s[12:13]
	v_mov_b32_e32 v0, 0x2000
	v_mov_b32_e32 v1, s3

.LBB0_1090:
	s_or_b64 exec, exec, s[16:17]
	v_cvt_f32_u32_e32 v4, v2
	s_waitcnt vmcnt(0)
	buffer_inv sc1
	v_readfirstlane_b32 s3, v3
	v_sub_u32_e32 v3, 0, v2
	v_rcp_iflag_f32_e32 v4, v4
	v_add_u32_e32 v5, s3, v1
	v_mul_f32_e32 v4, 0x4f7ffffe, v4
	v_cvt_u32_f32_e32 v4, v4
	v_mul_lo_u32 v1, v3, v4
	v_mul_hi_u32 v1, v4, v1
	v_add_u32_e32 v1, v4, v1
	v_mul_hi_u32 v1, v5, v1
	v_mul_lo_u32 v3, v1, v2
	v_sub_u32_e32 v3, v5, v3
	v_add_u32_e32 v4, 1, v1
	v_cmp_ge_u32_e32 vcc, v3, v2
	s_nop 1
	v_cndmask_b32_e32 v1, v1, v4, vcc
	v_sub_u32_e32 v4, v3, v2
	v_cndmask_b32_e32 v3, v3, v4, vcc
	v_add_u32_e32 v4, 1, v1
	v_cmp_ge_u32_e32 vcc, v3, v2
	v_add_u32_e32 v3, 1, v5
	s_nop 0
	v_cndmask_b32_e32 v1, v1, v4, vcc
	v_mul_lo_u32 v4, v2, v1
	v_add_u32_e32 v2, v4, v2
	v_cmp_ne_u32_e32 vcc, v3, v2
	s_and_saveexec_b64 s[6:7], vcc
	s_xor_b64 s[6:7], exec, s[6:7]
	s_cbranch_execz .LBB0_1104
	s_waitcnt lgkmcnt(0)
	v_add_u32_e32 v1, 1, v1
	v_mul_lo_u32 v1, v1, v0
	s_add_u32 s46, s24, 0xed25400
	s_addc_u32 s47, s25, 0
	v_mov_b32_e32 v0, 0
	global_load_dword v0, v0, s[46:47] sc1
	s_waitcnt vmcnt(0)
	v_cmp_lt_u32_e32 vcc, v0, v1
	s_and_saveexec_b64 s[40:41], vcc
	s_cbranch_execz .LBB0_1103
	s_add_u32 s42, s24, 0xed22200
	s_addc_u32 s43, s25, 0
	s_mov_b32 s3, 1
	s_mov_b64 s[48:49], 0
	v_mov_b32_e32 v0, 0
	s_branch .LBB0_1094

.LBB0_1103:
	s_or_b64 exec, exec, s[40:41]
	s_waitcnt vmcnt(0)
	s_waitcnt vmcnt(0)

.LBB0_1121:
	s_or_b64 exec, exec, s[28:29]
	s_mov_b64 s[16:17], exec
	v_mbcnt_lo_u32_b32 v0, s16, 0
	v_mbcnt_hi_u32_b32 v0, s17, v0
	v_cmp_eq_u32_e32 vcc, 0, v0
	s_waitcnt vmcnt(0)
	s_and_saveexec_b64 s[28:29], vcc
	s_cbranch_execz .LBB0_1123
	s_bcnt1_i32_b64 s3, s[16:17]
	v_mov_b32_e32 v0, 0x2000
	v_mov_b32_e32 v1, s3

.LBB0_1220:
	s_or_b64 exec, exec, s[16:17]
	v_cvt_f32_u32_e32 v4, v2
	s_waitcnt vmcnt(0)
	buffer_inv sc1
	v_readfirstlane_b32 s3, v3
	v_sub_u32_e32 v3, 0, v2
	v_rcp_iflag_f32_e32 v4, v4
	v_add_u32_e32 v5, s3, v1
	v_mul_f32_e32 v4, 0x4f7ffffe, v4
	v_cvt_u32_f32_e32 v4, v4
	v_mul_lo_u32 v1, v3, v4
	v_mul_hi_u32 v1, v4, v1
	v_add_u32_e32 v1, v4, v1
	v_mul_hi_u32 v1, v5, v1
	v_mul_lo_u32 v3, v1, v2
	v_sub_u32_e32 v3, v5, v3
	v_add_u32_e32 v4, 1, v1
	v_cmp_ge_u32_e32 vcc, v3, v2
	s_nop 1
	v_cndmask_b32_e32 v1, v1, v4, vcc
	v_sub_u32_e32 v4, v3, v2
	v_cndmask_b32_e32 v3, v3, v4, vcc
	v_add_u32_e32 v4, 1, v1
	v_cmp_ge_u32_e32 vcc, v3, v2
	v_add_u32_e32 v3, 1, v5
	s_nop 0
	v_cndmask_b32_e32 v1, v1, v4, vcc
	v_mul_lo_u32 v4, v2, v1
	v_add_u32_e32 v2, v4, v2
	v_cmp_ne_u32_e32 vcc, v3, v2
	s_and_saveexec_b64 s[6:7], vcc
	s_xor_b64 s[6:7], exec, s[6:7]
	s_cbranch_execz .LBB0_1234
	s_waitcnt lgkmcnt(0)
	v_add_u32_e32 v1, 1, v1
	v_mul_lo_u32 v1, v1, v0
	s_add_u32 s40, s24, 0xed25400
	s_addc_u32 s41, s25, 0
	v_mov_b32_e32 v0, 0
	global_load_dword v0, v0, s[40:41] sc1
	s_waitcnt vmcnt(0)
	v_cmp_lt_u32_e32 vcc, v0, v1
	s_and_saveexec_b64 s[36:37], vcc
	s_cbranch_execz .LBB0_1233
	s_add_u32 s38, s24, 0xed22200
	s_addc_u32 s39, s25, 0
	s_mov_b32 s3, 1
	s_mov_b64 s[42:43], 0
	v_mov_b32_e32 v0, 0
	s_branch .LBB0_1224

.LBB0_1233:
	s_or_b64 exec, exec, s[36:37]
	s_waitcnt vmcnt(0)
	s_waitcnt vmcnt(0)

.LBB0_1251:
	s_or_b64 exec, exec, s[6:7]
	s_mov_b64 s[6:7], exec
	v_mbcnt_lo_u32_b32 v0, s6, 0
	v_mbcnt_hi_u32_b32 v0, s7, v0
	v_cmp_eq_u32_e32 vcc, 0, v0
	s_waitcnt vmcnt(0)
	s_and_saveexec_b64 s[16:17], vcc
	s_cbranch_execz .LBB0_1253
	s_bcnt1_i32_b64 s3, s[6:7]
	v_mov_b32_e32 v0, 0x2000
	v_mov_b32_e32 v1, s3

.LBB0_1318:
	s_or_b64 exec, exec, s[14:15]
	v_cvt_f32_u32_e32 v4, v2
	s_waitcnt vmcnt(0)
	buffer_inv sc1
	v_readfirstlane_b32 s3, v3
	v_sub_u32_e32 v3, 0, v2
	v_rcp_iflag_f32_e32 v4, v4
	v_add_u32_e32 v5, s3, v1
	v_mul_f32_e32 v4, 0x4f7ffffe, v4
	v_cvt_u32_f32_e32 v4, v4
	v_mul_lo_u32 v1, v3, v4
	v_mul_hi_u32 v1, v4, v1
	v_add_u32_e32 v1, v4, v1
	v_mul_hi_u32 v1, v5, v1
	v_mul_lo_u32 v3, v1, v2
	v_sub_u32_e32 v3, v5, v3
	v_add_u32_e32 v4, 1, v1
	v_cmp_ge_u32_e32 vcc, v3, v2
	s_nop 1
	v_cndmask_b32_e32 v1, v1, v4, vcc
	v_sub_u32_e32 v4, v3, v2
	v_cndmask_b32_e32 v3, v3, v4, vcc
	v_add_u32_e32 v4, 1, v1
	v_cmp_ge_u32_e32 vcc, v3, v2
	v_add_u32_e32 v3, 1, v5
	s_nop 0
	v_cndmask_b32_e32 v1, v1, v4, vcc
	v_mul_lo_u32 v4, v2, v1
	v_add_u32_e32 v2, v4, v2
	v_cmp_ne_u32_e32 vcc, v3, v2
	s_and_saveexec_b64 s[6:7], vcc
	s_xor_b64 s[6:7], exec, s[6:7]
	s_cbranch_execz .LBB0_1332
	s_waitcnt lgkmcnt(0)
	v_add_u32_e32 v1, 1, v1
	v_mul_lo_u32 v1, v1, v0
	s_add_u32 s38, s24, 0xed25400
	s_addc_u32 s39, s25, 0
	v_mov_b32_e32 v0, 0
	global_load_dword v0, v0, s[38:39] sc1
	s_waitcnt vmcnt(0)
	v_cmp_lt_u32_e32 vcc, v0, v1
	s_and_saveexec_b64 s[14:15], vcc
	s_cbranch_execz .LBB0_1331
	s_add_u32 s36, s24, 0xed22200
	s_addc_u32 s37, s25, 0
	s_mov_b32 s3, 1
	s_mov_b64 s[40:41], 0
	v_mov_b32_e32 v0, 0
	s_branch .LBB0_1322

.LBB0_1331:
	s_or_b64 exec, exec, s[14:15]
	s_waitcnt vmcnt(0)
	s_waitcnt vmcnt(0)

.LBB0_1349:
	s_or_b64 exec, exec, s[14:15]
	s_mov_b64 s[14:15], exec
	v_mbcnt_lo_u32_b32 v0, s14, 0
	v_mbcnt_hi_u32_b32 v0, s15, v0
	v_cmp_eq_u32_e32 vcc, 0, v0
	s_waitcnt vmcnt(0)
	s_and_saveexec_b64 s[16:17], vcc
	s_cbranch_execz .LBB0_1351
	s_bcnt1_i32_b64 s3, s[14:15]
	v_mov_b32_e32 v0, 0x2000
	v_mov_b32_e32 v1, s3

.LBB0_1522:
	s_or_b64 exec, exec, s[8:9]
	v_cvt_f32_u32_e32 v4, v2
	s_waitcnt vmcnt(0)
	buffer_inv sc1
	v_readfirstlane_b32 s6, v3
	v_sub_u32_e32 v3, 0, v2
	v_rcp_iflag_f32_e32 v4, v4
	v_add_u32_e32 v5, s6, v1
	v_mul_f32_e32 v4, 0x4f7ffffe, v4
	v_cvt_u32_f32_e32 v4, v4
	v_mul_lo_u32 v1, v3, v4
	v_mul_hi_u32 v1, v4, v1
	v_add_u32_e32 v1, v4, v1
	v_mul_hi_u32 v1, v5, v1
	v_mul_lo_u32 v3, v1, v2
	v_sub_u32_e32 v3, v5, v3
	v_add_u32_e32 v4, 1, v1
	v_cmp_ge_u32_e32 vcc, v3, v2
	s_nop 1
	v_cndmask_b32_e32 v1, v1, v4, vcc
	v_sub_u32_e32 v4, v3, v2
	v_cndmask_b32_e32 v3, v3, v4, vcc
	v_add_u32_e32 v4, 1, v1
	v_cmp_ge_u32_e32 vcc, v3, v2
	v_add_u32_e32 v3, 1, v5
	s_nop 0
	v_cndmask_b32_e32 v1, v1, v4, vcc
	v_mul_lo_u32 v4, v2, v1
	v_add_u32_e32 v2, v4, v2
	v_cmp_ne_u32_e32 vcc, v3, v2
	s_and_saveexec_b64 s[6:7], vcc
	s_xor_b64 s[6:7], exec, s[6:7]
	s_cbranch_execz .LBB0_1536
	s_waitcnt lgkmcnt(0)
	v_add_u32_e32 v1, 1, v1
	v_mul_lo_u32 v1, v1, v0
	s_add_u32 s14, s24, 0xed25400
	s_addc_u32 s15, s25, 0
	v_mov_b32_e32 v0, 0
	global_load_dword v0, v0, s[14:15] sc1
	s_waitcnt vmcnt(0)
	v_cmp_lt_u32_e32 vcc, v0, v1
	s_and_saveexec_b64 s[8:9], vcc
	s_cbranch_execz .LBB0_1535
	s_add_u32 s12, s24, 0xed22200
	s_addc_u32 s13, s25, 0
	s_mov_b32 s19, 1
	s_mov_b64 s[16:17], 0
	v_mov_b32_e32 v0, 0
	s_branch .LBB0_1526

.LBB0_1553:
	s_or_b64 exec, exec, s[6:7]
	s_mov_b64 s[6:7], exec
	v_mbcnt_lo_u32_b32 v0, s6, 0
	v_mbcnt_hi_u32_b32 v0, s7, v0
	v_cmp_eq_u32_e32 vcc, 0, v0
	s_waitcnt vmcnt(0)
	s_and_saveexec_b64 s[8:9], vcc
	s_cbranch_execz .LBB0_1555
	s_bcnt1_i32_b64 s6, s[6:7]
	v_mov_b32_e32 v0, 0x2000
	v_mov_b32_e32 v1, s6
